# phase-D short-conv loop hand-rewritten: loop-invariant conv weights hoisted, 7 row loads issued together, next element prefetched
# baseline (speedup 1.0000x reference)
; __device__ __forceinline__ int tid_() { int t = threadIdx.x; asm volatile("" : "+v"(t)); return t; }
; __device__ __forceinline__ int bid_() { int t = blockIdx.x; asm volatile("" : "+s"(t)); return t; }
; __device__ __forceinline__ int nblk_() { int t = gridDim.x; asm volatile("" : "+s"(t)); return t; }
; __device__ __forceinline__ void conv_all(KArgs& a, int l) {
;     const size_t gt = (size_t)bid_() * 512 + tid_(), gn = (size_t)nblk_() * 512;
;     const bf16_t* PA = (const bf16_t*)(a.ws + OFF_R1); bf16_t* AC = (bf16_t*)(a.ws + OFF_R2);
;     const float* cw = a.conv_w + l * 3 * 512;
;     for (size_t e = gt; e < (size_t)MTOK * 64; e += gn) {
;         const int r = (int)(e >> 6), c0 = (int)(e & 63) * 8; const int t = r % TPB;
;         const bf16_t* pr = PA + (size_t)r * PALD + c0;
;         float xa[8], xb[8], xc[8], vm[8], vp[8];
;         unpack8(*(const u32x4*)pr, xa); unpack8(*(const u32x4*)(pr + 512), xb); unpack8(*(const u32x4*)(pr + 1024), xc);
;         const bool hasm = (t != 0 && t != CTXL), hasp = (t != CTXL - 1 && t != TPB - 1);
;         if (hasm) { float q1[8], q2[8]; unpack8(*(const u32x4*)(pr - PALD), q1); unpack8(*(const u32x4*)(pr - PALD + 1024), q2);
; #pragma unroll
;             for (int i = 0; i < 8; ++i) vm[i] = q1[i] * q2[i]; }
;         else {
; #pragma unroll
;             for (int i = 0; i < 8; ++i) vm[i] = 0.f; }
;         if (hasp) { float q1[8], q2[8]; unpack8(*(const u32x4*)(pr + PALD), q1); unpack8(*(const u32x4*)(pr + PALD + 1024), q2);
.LBB0_604:
	s_or_b64 exec, exec, s[22:23]
	s_mov_b32 s22, s84
	s_ashr_i32 s23, s22, 31
	v_mov_b32_e32 v2, v216
	s_lshl_b64 s[0:1], s[22:23], 9
	s_nop 0
	v_ashrrev_i32_e32 v3, 31, v2
	v_lshl_add_u64 v[14:15], s[0:1], 0, v[2:3]
	v_readlane_b32 s0, v237, 2
	v_readlane_b32 s1, v237, 3
	s_load_dwordx2 s[24:25], s[0:1], 0xf0
	s_mov_b64 s[0:1], 0x220000
	v_cmp_gt_u64_e32 vcc, s[0:1], v[14:15]
	s_waitcnt lgkmcnt(0)
	s_and_saveexec_b64 s[0:1], vcc
	s_cbranch_execz .LBB0_611
	s_ashr_i32 s25, s24, 31
	s_lshl_b64 s[8:9], s[24:25], 9
	s_load_dwordx2 s[2:3], s[14:15], 0x40
	s_add_u32 s14, s16, 0xcaf8000
	s_addc_u32 s15, s17, 0
	s_add_u32 s16, s16, 0x196f8000
	s_mulk_i32 s4, 0x600
	s_addc_u32 s17, s17, 0
	s_ashr_i32 s5, s4, 31
	s_lshl_b64 s[4:5], s[4:5], 2
	s_waitcnt lgkmcnt(0)
	s_add_u32 s4, s2, s4
	s_addc_u32 s5, s3, s5
	s_lshl_b64 s[2:3], s[22:23], 12
	v_lshl_add_u64 v[16:17], v[2:3], 3, s[2:3]
	s_lshl_b64 s[22:23], s[24:25], 12
	s_mov_b64 s[24:25], 0
	v_and_b32_e32 v38, 0x1f8, v16
	v_lshlrev_b32_e32 v36, 2, v38
	v_lshlrev_b32_e32 v0, 1, v38
	v_mov_b32_e32 v37, v1
	global_load_dwordx4 v[148:151], v36, s[4:5]
	global_load_dwordx4 v[152:155], v36, s[4:5] offset:16
	global_load_dwordx4 v[156:159], v36, s[4:5] offset:2048
	global_load_dwordx4 v[160:163], v36, s[4:5] offset:2064
	v_lshl_add_u64 v[44:45], s[4:5], 0, v[36:37]
	s_mov_b64 s[2:3], 0x1000
	v_lshl_add_u64 v[44:45], v[44:45], 0, s[2:3]
	global_load_dwordx4 v[164:167], v[44:45], off
	global_load_dwordx4 v[168:171], v[44:45], off offset:16
	v_lshrrev_b64 v[18:19], 6, v[14:15]
	v_lshlrev_b64 v[2:3], 12, v[18:19]
	v_lshl_add_u64 v[2:3], s[14:15], 0, v[2:3]
	v_lshl_add_u64 v[172:173], v[2:3], 0, v[0:1]
	global_load_dwordx4 v[176:179], v[172:173], off
	global_load_dwordx4 v[180:183], v[172:173], off offset:1024
	global_load_dwordx4 v[184:187], v[172:173], off offset:2048
	global_load_dwordx4 v[188:191], v[172:173], off offset:-4096
	global_load_dwordx4 v[192:195], v[172:173], off offset:-2048
	v_lshl_add_u64 v[2:3], v[172:173], 0, s[2:3]
	global_load_dwordx4 v[196:199], v[2:3], off
	global_load_dwordx4 v[200:203], v[2:3], off offset:2048
	s_waitcnt vmcnt(0)
.Lconv_loop:
	v_alignbit_b32 v213, v15, v14, 6
	v_mul_u32_u24_e32 v213, 0xf0f1, v213
	v_lshrrev_b32_e32 v213, 28, v213
	v_lshrrev_b32_e32 v212, 6, v14
	v_mul_lo_u16_e32 v213, 0x1100, v213
	v_sub_u16_e32 v214, v212, v213
	v_and_b32_e32 v212, 0x1eff, v214
	v_and_b32_e32 v214, 0xfff, v214
	v_lshlrev_b64 v[6:7], 10, v[18:19]
	v_lshl_add_u64 v[6:7], s[16:17], 0, v[6:7]
	v_lshl_add_u64 v[174:175], v[6:7], 0, v[0:1]
	v_lshlrev_b32_e32 v20, 16, v176
	v_and_b32_e32 v21, 0xffff0000, v176
	v_lshlrev_b32_e32 v22, 16, v177
	v_and_b32_e32 v23, 0xffff0000, v177
	v_lshlrev_b32_e32 v24, 16, v178
	v_and_b32_e32 v25, 0xffff0000, v178
	v_lshlrev_b32_e32 v26, 16, v179
	v_and_b32_e32 v27, 0xffff0000, v179
	v_lshlrev_b32_e32 v28, 16, v180
	v_and_b32_e32 v29, 0xffff0000, v180
	v_lshlrev_b32_e32 v30, 16, v181
	v_and_b32_e32 v31, 0xffff0000, v181
	v_lshlrev_b32_e32 v32, 16, v182
	v_and_b32_e32 v33, 0xffff0000, v182
	v_lshlrev_b32_e32 v34, 16, v183
	v_and_b32_e32 v35, 0xffff0000, v183
	v_lshlrev_b32_e32 v36, 16, v184
	v_and_b32_e32 v37, 0xffff0000, v184
	v_lshlrev_b32_e32 v38, 16, v185
	v_and_b32_e32 v39, 0xffff0000, v185
	v_lshlrev_b32_e32 v40, 16, v186
	v_and_b32_e32 v41, 0xffff0000, v186
	v_lshlrev_b32_e32 v42, 16, v187
	v_and_b32_e32 v43, 0xffff0000, v187
	v_lshlrev_b32_e32 v44, 16, v188
	v_and_b32_e32 v45, 0xffff0000, v188
	v_lshlrev_b32_e32 v46, 16, v189
	v_and_b32_e32 v47, 0xffff0000, v189
	v_lshlrev_b32_e32 v48, 16, v190
	v_and_b32_e32 v49, 0xffff0000, v190
	v_lshlrev_b32_e32 v50, 16, v191
	v_and_b32_e32 v51, 0xffff0000, v191
	v_lshlrev_b32_e32 v52, 16, v192
	v_and_b32_e32 v53, 0xffff0000, v192
	v_lshlrev_b32_e32 v54, 16, v193
	v_and_b32_e32 v55, 0xffff0000, v193
	v_lshlrev_b32_e32 v56, 16, v194
	v_and_b32_e32 v57, 0xffff0000, v194
	v_lshlrev_b32_e32 v58, 16, v195
	v_and_b32_e32 v59, 0xffff0000, v195
	v_lshlrev_b32_e32 v60, 16, v196
	v_and_b32_e32 v61, 0xffff0000, v196
	v_lshlrev_b32_e32 v62, 16, v197
	v_and_b32_e32 v63, 0xffff0000, v197
	v_lshlrev_b32_e32 v64, 16, v198
	v_and_b32_e32 v65, 0xffff0000, v198
	v_lshlrev_b32_e32 v66, 16, v199
	v_and_b32_e32 v67, 0xffff0000, v199
	v_lshlrev_b32_e32 v204, 16, v200
	v_and_b32_e32 v205, 0xffff0000, v200
	v_lshlrev_b32_e32 v206, 16, v201
	v_and_b32_e32 v207, 0xffff0000, v201
	v_lshlrev_b32_e32 v208, 16, v202
	v_and_b32_e32 v209, 0xffff0000, v202
	v_lshlrev_b32_e32 v210, 16, v203
	v_and_b32_e32 v211, 0xffff0000, v203
	v_cmp_ne_u32_e32 vcc, 0, v212
	s_cbranch_vccz .Lconv_nom
	v_pk_mul_f32 v[44:45], v[44:45], v[52:53]
	v_pk_mul_f32 v[46:47], v[46:47], v[54:55]
	v_pk_mul_f32 v[48:49], v[48:49], v[56:57]
	v_pk_mul_f32 v[50:51], v[50:51], v[58:59]
	s_branch .Lconv_m_done
; __device__ __forceinline__ unsigned pk2(float lo, float hi) { const f32x2 v = {lo, hi}; return __builtin_bit_cast(unsigned, __builtin_convertvector(v, bf16v2_t)); }
; __device__ __forceinline__ void xcd_barrier(const XcdBarrier& b) {
;     asm volatile("s_waitcnt vmcnt(0)" ::: "memory");
;     __syncthreads();
;     if (threadIdx.x == 0) {
;         unsigned* bar = b.bar;
;         __builtin_amdgcn_s_waitcnt(0);
;         unsigned nloc = b.st[0], nx = b.st[1];
;         if (nloc == 0u) { xcd_barrier_complete(bar, b.x, nloc, nx); b.st[0] = nloc; b.st[1] = nx; }
; __device__ __forceinline__ void conv_all(KArgs& a, int l) {
;     ...
;         const bool hasm = (t != 0 && t != CTXL), hasp = (t != CTXL - 1 && t != TPB - 1);
;         if (hasm) { float q1[8], q2[8]; unpack8(*(const u32x4*)(pr - PALD), q1); unpack8(*(const u32x4*)(pr - PALD + 1024), q2);
; #pragma unroll
;             for (int i = 0; i < 8; ++i) vm[i] = q1[i] * q2[i]; }
;         else {
; #pragma unroll
;             for (int i = 0; i < 8; ++i) vm[i] = 0.f; }
;         if (hasp) { float q1[8], q2[8]; unpack8(*(const u32x4*)(pr + PALD), q1); unpack8(*(const u32x4*)(pr + PALD + 1024), q2);
; #pragma unroll
;             for (int i = 0; i < 8; ++i) vp[i] = q1[i] * q2[i]; }
;         else {
; #pragma unroll
;             for (int i = 0; i < 8; ++i) vp[i] = 0.f; }
;         float o[8];
; #pragma unroll
;         for (int i = 0; i < 8; ++i) o[i] = xb[i] * (cw[c0 + i] * vm[i] + cw[512 + c0 + i] * (xa[i] * xc[i]) + cw[1024 + c0 + i] * vp[i]);
;         u32x4 ov; ov.x = pk2(o[0], o[1]); ov.y = pk2(o[2], o[3]); ov.z = pk2(o[4], o[5]); ov.w = pk2(o[6], o[7]);
;         *(u32x4*)(AC + (size_t)r * 512 + c0) = ov;
;     }
.Lconv_nom:
	v_mov_b64_e32 v[44:45], 0
	v_mov_b64_e32 v[46:47], 0
	v_mov_b64_e32 v[48:49], 0
	v_mov_b64_e32 v[50:51], 0
.Lconv_m_done:
	v_cmp_ne_u32_e32 vcc, s90, v214
	s_cbranch_vccz .Lconv_nop
	v_pk_mul_f32 v[60:61], v[60:61], v[204:205]
	v_pk_mul_f32 v[62:63], v[62:63], v[206:207]
	v_pk_mul_f32 v[64:65], v[64:65], v[208:209]
	v_pk_mul_f32 v[66:67], v[66:67], v[210:211]
	s_branch .Lconv_p_done
.Lconv_nop:
	v_mov_b64_e32 v[60:61], 0
	v_mov_b64_e32 v[62:63], 0
	v_mov_b64_e32 v[64:65], 0
	v_mov_b64_e32 v[66:67], 0
.Lconv_p_done:
	v_lshl_add_u64 v[14:15], v[14:15], 0, s[8:9]
	v_lshl_add_u64 v[16:17], v[16:17], 0, s[22:23]
	s_mov_b64 s[2:3], 0x21ffff
	v_cmp_lt_u64_e32 vcc, s[2:3], v[14:15]
	s_mov_b64 s[2:3], 0x1000
	s_cbranch_vccnz .Lconv_math
	v_lshrrev_b64 v[18:19], 6, v[14:15]
	v_lshlrev_b64 v[2:3], 12, v[18:19]
	v_lshl_add_u64 v[2:3], s[14:15], 0, v[2:3]
	v_lshl_add_u64 v[172:173], v[2:3], 0, v[0:1]
	global_load_dwordx4 v[176:179], v[172:173], off
	global_load_dwordx4 v[180:183], v[172:173], off offset:1024
	global_load_dwordx4 v[184:187], v[172:173], off offset:2048
	global_load_dwordx4 v[188:191], v[172:173], off offset:-4096
	global_load_dwordx4 v[192:195], v[172:173], off offset:-2048
	v_lshl_add_u64 v[2:3], v[172:173], 0, s[2:3]
	global_load_dwordx4 v[196:199], v[2:3], off
	global_load_dwordx4 v[200:203], v[2:3], off offset:2048
.Lconv_math:
	v_pk_mul_f32 v[4:5], v[20:21], v[36:37]
	v_pk_mul_f32 v[6:7], v[22:23], v[38:39]
	v_pk_mul_f32 v[8:9], v[24:25], v[40:41]
	v_pk_mul_f32 v[10:11], v[26:27], v[42:43]
	v_pk_mul_f32 v[4:5], v[4:5], v[156:157]
	v_pk_mul_f32 v[6:7], v[6:7], v[158:159]
	v_pk_mul_f32 v[8:9], v[8:9], v[160:161]
	v_pk_mul_f32 v[10:11], v[10:11], v[162:163]
	v_pk_fma_f32 v[4:5], v[44:45], v[148:149], v[4:5]
	v_pk_fma_f32 v[6:7], v[46:47], v[150:151], v[6:7]
	v_pk_fma_f32 v[8:9], v[48:49], v[152:153], v[8:9]
	v_pk_fma_f32 v[10:11], v[50:51], v[154:155], v[10:11]
	v_pk_fma_f32 v[4:5], v[60:61], v[164:165], v[4:5]
	v_pk_fma_f32 v[6:7], v[62:63], v[166:167], v[6:7]
	v_pk_fma_f32 v[8:9], v[64:65], v[168:169], v[8:9]
	v_pk_fma_f32 v[10:11], v[66:67], v[170:171], v[10:11]
	v_pk_mul_f32 v[4:5], v[4:5], v[28:29]
	v_pk_mul_f32 v[6:7], v[6:7], v[30:31]
	v_pk_mul_f32 v[8:9], v[8:9], v[32:33]
	v_pk_mul_f32 v[10:11], v[10:11], v[34:35]
	s_nop 0
	v_cvt_pk_bf16_f32 v20, v4, v5
	v_cvt_pk_bf16_f32 v21, v6, v7
	v_cvt_pk_bf16_f32 v22, v8, v9
	v_cvt_pk_bf16_f32 v23, v10, v11
	global_store_dwordx4 v[174:175], v[20:23], off
	s_mov_b64 s[24:25], 0x21ffff
	v_cmp_lt_u64_e32 vcc, s[24:25], v[14:15]
	s_cbranch_vccnz .Lconv_done
	s_waitcnt vmcnt(1)
	s_branch .Lconv_loop
.Lconv_done:
.LBB0_611:
	s_or_b64 exec, exec, s[0:1]
	s_add_i32 s2, s87, 4
	s_cmp_ge_i32 s2, s51
	s_cbranch_scc1 .LBB0_678
	v_readlane_b32 s4, v237, 6
	v_readlane_b32 s5, v237, 7
	s_mov_b64 s[0:1], -1
	s_and_b64 vcc, exec, s[4:5]
	s_cbranch_vccz .LBB0_666
	s_waitcnt vmcnt(0)
	s_waitcnt vmcnt(0)
	s_barrier
	s_and_saveexec_b64 s[0:1], s[92:93]
	s_cbranch_execz .LBB0_665
	v_readlane_b32 s3, v236, 19
	s_waitcnt vmcnt(0) expcnt(0) lgkmcnt(0)
	s_nop 0
	v_mov_b32_e32 v0, s3
	ds_read_b32 v3, v0
	v_readlane_b32 s3, v236, 20
	s_waitcnt lgkmcnt(0)
	v_cmp_ne_u32_e32 vcc, 0, v3
	v_mov_b32_e32 v0, s3
	ds_read_b32 v2, v0
	s_cbranch_vccnz .LBB0_629
	s_mov_b32 s3, 1
	s_branch .LBB0_617
